# v43: v34 without the acquire cache invalidate after the spin in the two row-sum exchanges of the output-projection epilogue (the exchanged values are read with sc1 loads; nothing else depends on that
# speedup vs baseline: 1.0141x; 1.0130x over previous
.LBB0_638:
.LBB0_639:
	s_waitcnt vmcnt(0) lgkmcnt(0)
	s_barrier
	s_and_saveexec_b64 s[22:23], s[4:5]
	s_cbranch_execz .LBB0_641
	global_load_dword v133, v[0:1], off sc1
	global_load_dword v134, v[0:1], off offset:4 sc1
	global_load_dword v135, v[0:1], off offset:8 sc1
	s_nop 0
	global_load_dword v0, v[0:1], off offset:12 sc1
	v_lshl_add_u32 v1, v226, 2, 16
	s_waitcnt vmcnt(3)
	v_add_f32_e32 v133, 0, v133
	s_waitcnt vmcnt(2)
	v_add_f32_e32 v133, v133, v134
	s_waitcnt vmcnt(1)
	v_add_f32_e32 v133, v133, v135
	s_waitcnt vmcnt(0)
	v_add_f32_e32 v0, v133, v0
	ds_write_b32 v1, v0 offset:4096

.LBB0_718:
	s_waitcnt lgkmcnt(0)
.LBB0_719:
	s_waitcnt vmcnt(0) lgkmcnt(0)
	s_barrier
	s_and_saveexec_b64 s[0:1], s[4:5]
	s_cbranch_execz .LBB0_721
	global_load_dword v3, v[4:5], off sc1
	s_waitcnt lgkmcnt(7)
	global_load_dword v6, v[4:5], off offset:4 sc1
	s_waitcnt lgkmcnt(6)
	global_load_dword v7, v[4:5], off offset:8 sc1
	s_nop 0
	global_load_dword v4, v[4:5], off offset:12 sc1
	s_waitcnt vmcnt(3)
	v_add_f32_e32 v3, 0, v3
	s_waitcnt vmcnt(2)
	v_add_f32_e32 v3, v3, v6
	s_waitcnt vmcnt(1)
	v_add_f32_e32 v3, v3, v7
	s_waitcnt vmcnt(0)
	v_add_f32_e32 v3, v3, v4
	v_lshl_add_u32 v4, v226, 2, 16
	ds_write_b32 v4, v3 offset:4096
